# v19 + the sample-row slab summation between the merge GEMM and the out-projection (it sits between two grid barriers) de-serialised: all 32 slab loads issued up front, one wait (was 4 loads-wait-store
# baseline (speedup 1.0000x reference)
; #define GAS __attribute__((address_space(1)))
; __device__ __forceinline__ unsigned cvt_pk4_fp8(float a, float b, float c, float d) { int w = __builtin_amdgcn_cvt_pk_fp8_f32(fp8_clamp(a), fp8_clamp(b), 0, false); w = __builtin_amdgcn_cvt_pk_fp8_f32(fp8_clamp(c), fp8_clamp(d), w, true); return (unsigned)w; }
; #define TIDS() const int lane = lane_id(), tid = wave * 64 + lane; (void)tid; (void)lane
; __global__ void __launch_bounds__(NTHREADS, 2) fwd_kernel(Args args) {
;     ...
;     if (IN(5)) {
;         TIDS();
;         if (gw < MS) { const float* sl = (const float*)(ws + WS_SLAB4) + (size_t)gw * DM;
; #pragma unroll
;             for (int j = 0; j < 8; ++j) { f32x4 t = ((const GAS f32x4*)sl + lane)[64 * j];
; #pragma unroll
;                 for (int sp = 1; sp < 4; ++sp) t += ((const GAS f32x4*)(sl + (size_t)sp * MS * DM) + lane)[64 * j];
;                 *((GAS unsigned*)(ws + WS_M8 + (size_t)(MP + gw) * DM) + 64 * j + lane) = cvt_pk4_fp8(t.x * M_SCALE, t.y * M_SCALE, t.z * M_SCALE, t.w * M_SCALE); } }
.LBB0_2220:
	s_cmp_lt_i32 s92, 6
	s_cselect_b64 s[8:9], -1, 0
	s_and_b64 s[6:7], s[8:9], s[6:7]
	s_andn2_b64 vcc, exec, s[6:7]
	s_cbranch_vccnz .LBB0_2301
	v_readlane_b32 s8, v255, 7
	s_cmpk_gt_i32 s8, 0x1ff
	v_readlane_b32 s9, v255, 8
	v_mbcnt_lo_u32_b32 v8, -1, 0
	v_mbcnt_hi_u32_b32 v8, -1, v8
	s_cbranch_scc1 .LBB0_2223
	v_readlane_b32 s8, v255, 7
	v_readlane_b32 s9, v255, 8
	s_mov_b32 s16, s8
	s_ashr_i32 s17, s8, 31
	s_lshl_b64 s[8:9], s[16:17], 13
	s_add_u32 s8, s46, s8
	s_addc_u32 s9, s47, s9
	v_ashrrev_i32_e32 v9, 31, v8
	v_lshl_add_u64 v[26:27], v[8:9], 4, s[8:9]
	s_mov_b32 s3, 0x14501000
	v_add_co_u32_e32 v0, vcc, s3, v26
	s_mov_b32 s3, 0x14901000
	s_nop 0
	v_addc_co_u32_e32 v1, vcc, 0, v27, vcc
	v_add_co_u32_e32 v2, vcc, s3, v26
	s_mov_b32 s3, 0x14d01000
	s_nop 0
	v_addc_co_u32_e32 v3, vcc, 0, v27, vcc
	v_add_co_u32_e32 v4, vcc, s3, v26
	s_mov_b32 s3, 0x15101000
	s_nop 0
	v_addc_co_u32_e32 v5, vcc, 0, v27, vcc
	v_add_co_u32_e32 v6, vcc, s3, v26
	s_nop 0
	v_addc_co_u32_e32 v7, vcc, 0, v27, vcc
	global_load_dwordx4 v[40:43], v[0:1], off offset:-4096
	global_load_dwordx4 v[44:47], v[2:3], off offset:-4096
	global_load_dwordx4 v[48:51], v[4:5], off offset:-4096
	global_load_dwordx4 v[52:55], v[6:7], off offset:-4096
	global_load_dwordx4 v[56:59], v[0:1], off offset:-3072
	global_load_dwordx4 v[60:63], v[2:3], off offset:-3072
	global_load_dwordx4 v[64:67], v[4:5], off offset:-3072
	global_load_dwordx4 v[68:71], v[6:7], off offset:-3072
	global_load_dwordx4 v[72:75], v[0:1], off offset:-2048
	global_load_dwordx4 v[76:79], v[2:3], off offset:-2048
	global_load_dwordx4 v[80:83], v[4:5], off offset:-2048
	global_load_dwordx4 v[84:87], v[6:7], off offset:-2048
	global_load_dwordx4 v[88:91], v[0:1], off offset:-1024
	global_load_dwordx4 v[92:95], v[2:3], off offset:-1024
	global_load_dwordx4 v[96:99], v[4:5], off offset:-1024
	global_load_dwordx4 v[100:103], v[6:7], off offset:-1024
	global_load_dwordx4 v[104:107], v[0:1], off
	global_load_dwordx4 v[108:111], v[2:3], off
	global_load_dwordx4 v[112:115], v[4:5], off
	global_load_dwordx4 v[116:119], v[6:7], off
	global_load_dwordx4 v[120:123], v[0:1], off offset:1024
	global_load_dwordx4 v[124:127], v[2:3], off offset:1024
	global_load_dwordx4 v[128:131], v[4:5], off offset:1024
	global_load_dwordx4 v[132:135], v[6:7], off offset:1024
	global_load_dwordx4 v[136:139], v[0:1], off offset:2048
	global_load_dwordx4 v[140:143], v[2:3], off offset:2048
	global_load_dwordx4 v[144:147], v[4:5], off offset:2048
	global_load_dwordx4 v[148:151], v[6:7], off offset:2048
	global_load_dwordx4 v[152:155], v[0:1], off offset:3072
	global_load_dwordx4 v[156:159], v[2:3], off offset:3072
	global_load_dwordx4 v[160:163], v[4:5], off offset:3072
	global_load_dwordx4 v[164:167], v[6:7], off offset:3072
	s_mov_b32 s10, s16
	v_writelane_b32 v255, s10, 7
	s_mov_b32 s3, 0xc3e00000
	v_mov_b32_e32 v36, 0x43e00000
	v_writelane_b32 v255, s11, 8
	s_lshl_b64 s[10:11], s[16:17], 11
	s_add_u32 s10, s46, s10
	s_addc_u32 s11, s47, s11
	v_mov_b32_e32 v37, 0
	v_lshl_add_u64 v[34:35], v[8:9], 2, s[10:11]
	s_mov_b32 s12, 0x14900000
	v_add_co_u32_e32 v30, vcc, s12, v26
	s_mov_b32 s13, 0x14d00000
	s_nop 0
	v_addc_co_u32_e32 v31, vcc, 0, v27, vcc
	v_add_co_u32_e32 v32, vcc, s13, v26
	s_mov_b32 s15, 0x1c600000
	s_waitcnt lgkmcnt(0)
	v_addc_co_u32_e32 v33, vcc, 0, v27, vcc
	s_mov_b64 s[8:9], 0x14500000
	s_mov_b32 s14, 0x15100000
	v_lshl_add_u64 v[28:29], v[26:27], 0, s[8:9]
	s_mov_b64 s[8:9], 0x1c600000
	s_waitcnt vmcnt(0)
; #define GAS __attribute__((address_space(1)))
; __device__ __forceinline__ unsigned cvt_pk4_fp8(float a, float b, float c, float d) { int w = __builtin_amdgcn_cvt_pk_fp8_f32(fp8_clamp(a), fp8_clamp(b), 0, false); w = __builtin_amdgcn_cvt_pk_fp8_f32(fp8_clamp(c), fp8_clamp(d), w, true); return (unsigned)w; }
; __global__ void __launch_bounds__(NTHREADS, 2) fwd_kernel(Args args) {
;     ...
;         if (gw < MS) { const float* sl = (const float*)(ws + WS_SLAB4) + (size_t)gw * DM;
; #pragma unroll
;             for (int j = 0; j < 8; ++j) { f32x4 t = ((const GAS f32x4*)sl + lane)[64 * j];
; #pragma unroll
;                 for (int sp = 1; sp < 4; ++sp) t += ((const GAS f32x4*)(sl + (size_t)sp * MS * DM) + lane)[64 * j];
;                 *((GAS unsigned*)(ws + WS_M8 + (size_t)(MP + gw) * DM) + 64 * j + lane) = cvt_pk4_fp8(t.x * M_SCALE, t.y * M_SCALE, t.z * M_SCALE, t.w * M_SCALE); } }
	v_pk_add_f32 v[10:11], v[40:41], v[44:45]
	v_pk_add_f32 v[8:9], v[42:43], v[46:47]
	v_pk_add_f32 v[10:11], v[10:11], v[48:49]
	v_pk_add_f32 v[8:9], v[8:9], v[50:51]
	v_pk_add_f32 v[10:11], v[10:11], v[52:53]
	s_nop 0
	v_mul_f32_e32 v10, 0x41800000, v10
	v_mul_f32_e32 v11, 0x41800000, v11
	v_med3_f32 v10, v10, s3, v36
	v_med3_f32 v11, v11, s3, v36
	v_cvt_pk_fp8_f32 v37, v10, v11
	v_pk_add_f32 v[8:9], v[8:9], v[54:55]
	v_mov_b32_e32 v24, 0
	v_mul_f32_e32 v8, 0x41800000, v8
	v_mul_f32_e32 v9, 0x41800000, v9
	v_med3_f32 v8, v8, s3, v36
	v_med3_f32 v9, v9, s3, v36
	v_cvt_pk_fp8_f32 v37, v8, v9 op_sel:[0, 0, 1]
	v_add_co_u32_e32 v8, vcc, s15, v34
	s_nop 1
	v_addc_co_u32_e32 v9, vcc, 0, v35, vcc
	global_store_dword v[8:9], v37, off
	v_add_co_u32_e32 v26, vcc, s14, v26
	v_addc_co_u32_e32 v27, vcc, 0, v27, vcc
	v_pk_add_f32 v[8:9], v[56:57], v[60:61]
	v_pk_add_f32 v[8:9], v[8:9], v[64:65]
	v_pk_add_f32 v[10:11], v[58:59], v[62:63]
	v_pk_add_f32 v[8:9], v[8:9], v[68:69]
	s_nop 0
	v_mul_f32_e32 v8, 0x41800000, v8
	v_mul_f32_e32 v9, 0x41800000, v9
	v_med3_f32 v8, v8, s3, v36
	v_med3_f32 v9, v9, s3, v36
	v_pk_add_f32 v[10:11], v[10:11], v[66:67]
	v_cvt_pk_fp8_f32 v24, v8, v9
	v_pk_add_f32 v[10:11], v[10:11], v[70:71]
	s_nop 0
	v_mul_f32_e32 v10, 0x41800000, v10
	v_mul_f32_e32 v8, 0x41800000, v11
	v_med3_f32 v9, v10, s3, v36
	v_med3_f32 v8, v8, s3, v36
	v_cvt_pk_fp8_f32 v24, v9, v8 op_sel:[0, 0, 1]
	v_lshl_add_u64 v[8:9], v[34:35], 0, s[8:9]
	v_mov_b32_e32 v34, 0
	global_store_dword v[8:9], v24, off offset:256
	s_nop 0
	v_pk_add_f32 v[10:11], v[72:73], v[76:77]
	v_pk_add_f32 v[10:11], v[10:11], v[80:81]
	v_pk_add_f32 v[12:13], v[74:75], v[78:79]
	v_pk_add_f32 v[10:11], v[10:11], v[84:85]
	v_pk_add_f32 v[12:13], v[12:13], v[82:83]
	v_mul_f32_e32 v10, 0x41800000, v10
	v_mul_f32_e32 v11, 0x41800000, v11
	v_med3_f32 v10, v10, s3, v36
	v_med3_f32 v11, v11, s3, v36
	v_cvt_pk_fp8_f32 v34, v10, v11
	v_pk_add_f32 v[12:13], v[12:13], v[86:87]
	s_nop 0
	v_mul_f32_e32 v12, 0x41800000, v12
	v_mul_f32_e32 v10, 0x41800000, v13
	v_med3_f32 v11, v12, s3, v36
	v_med3_f32 v10, v10, s3, v36
	v_cvt_pk_fp8_f32 v34, v11, v10 op_sel:[0, 0, 1]
	global_store_dword v[8:9], v34, off offset:512
	v_mov_b32_e32 v26, 0
	v_pk_add_f32 v[10:11], v[88:89], v[92:93]
	v_pk_add_f32 v[10:11], v[10:11], v[96:97]
	v_pk_add_f32 v[12:13], v[90:91], v[94:95]
	v_pk_add_f32 v[10:11], v[10:11], v[100:101]
	v_pk_add_f32 v[12:13], v[12:13], v[98:99]
	v_mul_f32_e32 v10, 0x41800000, v10
	v_mul_f32_e32 v11, 0x41800000, v11
	v_med3_f32 v10, v10, s3, v36
	v_med3_f32 v11, v11, s3, v36
	v_cvt_pk_fp8_f32 v26, v10, v11
	v_pk_add_f32 v[12:13], v[12:13], v[102:103]
	s_nop 0
	v_mul_f32_e32 v12, 0x41800000, v12
	v_mul_f32_e32 v10, 0x41800000, v13
	v_med3_f32 v11, v12, s3, v36
	v_med3_f32 v10, v10, s3, v36
	v_cvt_pk_fp8_f32 v26, v11, v10 op_sel:[0, 0, 1]
	global_store_dword v[8:9], v26, off offset:768
	v_mov_b32_e32 v26, 0
	v_pk_add_f32 v[10:11], v[104:105], v[108:109]
	v_pk_add_f32 v[10:11], v[10:11], v[112:113]
	v_pk_add_f32 v[12:13], v[106:107], v[110:111]
	v_pk_add_f32 v[10:11], v[10:11], v[116:117]
	v_pk_add_f32 v[12:13], v[12:13], v[114:115]
	v_mul_f32_e32 v10, 0x41800000, v10
	v_mul_f32_e32 v11, 0x41800000, v11
	v_med3_f32 v10, v10, s3, v36
	v_med3_f32 v11, v11, s3, v36
	v_cvt_pk_fp8_f32 v26, v10, v11
	v_pk_add_f32 v[12:13], v[12:13], v[118:119]
	s_nop 0
	v_mul_f32_e32 v12, 0x41800000, v12
	v_mul_f32_e32 v10, 0x41800000, v13
	v_med3_f32 v11, v12, s3, v36
	v_med3_f32 v10, v10, s3, v36
	v_cvt_pk_fp8_f32 v26, v11, v10 op_sel:[0, 0, 1]
	global_store_dword v[8:9], v26, off offset:1024
	v_mov_b32_e32 v26, 0
	v_pk_add_f32 v[10:11], v[120:121], v[124:125]
	v_pk_add_f32 v[10:11], v[10:11], v[128:129]
	v_pk_add_f32 v[12:13], v[122:123], v[126:127]
	v_pk_add_f32 v[10:11], v[10:11], v[132:133]
	v_pk_add_f32 v[12:13], v[12:13], v[130:131]
	v_mul_f32_e32 v10, 0x41800000, v10
	v_mul_f32_e32 v11, 0x41800000, v11
	v_med3_f32 v10, v10, s3, v36
	v_med3_f32 v11, v11, s3, v36
	v_cvt_pk_fp8_f32 v26, v10, v11
	v_pk_add_f32 v[12:13], v[12:13], v[134:135]
	s_nop 0
	v_mul_f32_e32 v12, 0x41800000, v12
	v_mul_f32_e32 v10, 0x41800000, v13
	v_med3_f32 v11, v12, s3, v36
	v_med3_f32 v10, v10, s3, v36
	v_cvt_pk_fp8_f32 v26, v11, v10 op_sel:[0, 0, 1]
	global_store_dword v[8:9], v26, off offset:1280
	v_mov_b32_e32 v26, 0
	v_pk_add_f32 v[10:11], v[136:137], v[140:141]
	v_pk_add_f32 v[10:11], v[10:11], v[144:145]
	v_pk_add_f32 v[12:13], v[138:139], v[142:143]
	v_pk_add_f32 v[10:11], v[10:11], v[148:149]
	v_pk_add_f32 v[12:13], v[12:13], v[146:147]
	v_mul_f32_e32 v10, 0x41800000, v10
	v_mul_f32_e32 v11, 0x41800000, v11
	v_med3_f32 v10, v10, s3, v36
	v_med3_f32 v11, v11, s3, v36
	v_cvt_pk_fp8_f32 v26, v10, v11
	v_pk_add_f32 v[12:13], v[12:13], v[150:151]
	s_nop 0
	v_mul_f32_e32 v12, 0x41800000, v12
	v_mul_f32_e32 v10, 0x41800000, v13
	v_med3_f32 v11, v12, s3, v36
	v_med3_f32 v10, v10, s3, v36
	v_cvt_pk_fp8_f32 v26, v11, v10 op_sel:[0, 0, 1]
	global_store_dword v[8:9], v26, off offset:1536
	v_mov_b32_e32 v4, 0
	v_pk_add_f32 v[2:3], v[152:153], v[156:157]
	v_pk_add_f32 v[2:3], v[2:3], v[160:161]
	v_pk_add_f32 v[0:1], v[154:155], v[158:159]
	v_pk_add_f32 v[2:3], v[2:3], v[164:165]
	v_pk_add_f32 v[0:1], v[0:1], v[162:163]
	v_mul_f32_e32 v2, 0x41800000, v2
	v_mul_f32_e32 v3, 0x41800000, v3
	v_med3_f32 v2, v2, s3, v36
	v_med3_f32 v3, v3, s3, v36
	v_cvt_pk_fp8_f32 v4, v2, v3
	v_pk_add_f32 v[0:1], v[0:1], v[166:167]
	s_nop 0
	v_mul_f32_e32 v0, 0x41800000, v0
	v_mul_f32_e32 v1, 0x41800000, v1
	v_med3_f32 v0, v0, s3, v36
	v_med3_f32 v1, v1, s3, v36
	v_cvt_pk_fp8_f32 v4, v0, v1 op_sel:[0, 0, 1]
	global_store_dword v[8:9], v4, off offset:1792
